# m23 + non-temporal hint on the attention-unit MIX output stores
# speedup vs baseline: 1.0016x; 1.0006x over previous
; __device__ __forceinline__ void attn_unit(LAS unsigned char* lds, const bf16_t* __restrict__ U3, const bf16_t* __restrict__ VT, bf16_t* __restrict__ MIX, ...
;     ...
;     if (c == 0) { float ss = 0.f;
; #pragma unroll
;         for (int d0 = 0; d0 < 4; ++d0)
; #pragma unroll
;             for (int r = 0; r < 16; ++r) { const float v = o[d0][r] * inv - comb[(32 * d0 + (r & 3) + 8 * (r >> 2) + 4 * hi) * 32]; o[d0][r] = v; ss += v * v; }
.LBB0_539:
	s_cmpk_gt_u32 s73, 0xff
	s_waitcnt vmcnt(0) lgkmcnt(0)
	s_barrier
	s_cbranch_scc1 .LBB0_498
	ds_read2_b32 v[84:85], v77 offset1:32
	s_mulk_i32 s72, 0x2200
	s_add_i32 s10, s72, 0
	s_add_i32 s10, s10, 0x10000
	s_waitcnt lgkmcnt(0)
	v_fma_f32 v66, v48, v64, -v84
	v_fma_f32 v65, v49, v64, -v85
	ds_read2_b32 v[48:49], v77 offset0:64 offset1:96
	v_mul_f32_e32 v83, v65, v65
	v_fmac_f32_e32 v83, v66, v66
	s_waitcnt lgkmcnt(0)
	v_fma_f32 v50, v50, v64, -v48
	v_fma_f32 v51, v51, v64, -v49
	ds_read2_b32 v[48:49], v76 offset1:32
	v_fmac_f32_e32 v83, v50, v50
	v_fmac_f32_e32 v83, v51, v51
	s_waitcnt lgkmcnt(0)
	v_fma_f32 v48, v52, v64, -v48
	v_fma_f32 v49, v53, v64, -v49
	ds_read2_b32 v[52:53], v76 offset0:64 offset1:96
	ds_read2_b32 v[76:77], v67 offset1:32
	v_fmac_f32_e32 v83, v48, v48
	v_fmac_f32_e32 v83, v49, v49
	s_waitcnt lgkmcnt(1)
	v_fma_f32 v52, v54, v64, -v52
	v_fma_f32 v53, v55, v64, -v53
	s_waitcnt lgkmcnt(0)
	v_fma_f32 v55, v56, v64, -v76
	v_fma_f32 v54, v57, v64, -v77
	ds_read2_b32 v[56:57], v67 offset0:64 offset1:96
	ds_read2_b32 v[76:77], v75 offset1:32
	v_fmac_f32_e32 v83, v52, v52
	v_fmac_f32_e32 v83, v53, v53
	v_fmac_f32_e32 v83, v55, v55
	s_waitcnt lgkmcnt(1)
	v_fma_f32 v67, v58, v64, -v56
	v_fma_f32 v58, v59, v64, -v57
	s_waitcnt lgkmcnt(0)
	v_fma_f32 v57, v60, v64, -v76
	v_fma_f32 v56, v61, v64, -v77
	ds_read2_b32 v[76:77], v75 offset0:64 offset1:96
	v_fmac_f32_e32 v83, v54, v54
	v_fmac_f32_e32 v83, v67, v67
	v_fmac_f32_e32 v83, v58, v58
	v_fmac_f32_e32 v83, v57, v57
	s_waitcnt lgkmcnt(0)
	v_fma_f32 v61, v62, v64, -v76
	v_fma_f32 v60, v63, v64, -v77
	ds_read2_b32 v[62:63], v74 offset1:32
	ds_read2_b32 v[74:75], v74 offset0:64 offset1:96
	v_fmac_f32_e32 v83, v56, v56
	v_fmac_f32_e32 v83, v61, v61
	v_fmac_f32_e32 v83, v60, v60
	s_waitcnt lgkmcnt(1)
	v_fma_f32 v59, v32, v64, -v62
	v_fma_f32 v32, v33, v64, -v63
	s_waitcnt lgkmcnt(0)
	v_fma_f32 v63, v34, v64, -v74
	v_fma_f32 v62, v35, v64, -v75
	ds_read2_b32 v[34:35], v68 offset1:32
	v_fmac_f32_e32 v83, v59, v59
	v_fmac_f32_e32 v83, v32, v32
	v_fmac_f32_e32 v83, v63, v63
	v_fmac_f32_e32 v83, v62, v62
	s_waitcnt lgkmcnt(0)
	v_fma_f32 v34, v36, v64, -v34
	v_fma_f32 v33, v37, v64, -v35
	ds_read2_b32 v[36:37], v68 offset0:64 offset1:96
	v_fmac_f32_e32 v83, v34, v34
	v_fmac_f32_e32 v83, v33, v33
	s_waitcnt lgkmcnt(0)
	v_fma_f32 v68, v38, v64, -v36
	v_fma_f32 v38, v39, v64, -v37
	ds_read2_b32 v[36:37], v69 offset1:32
	v_fmac_f32_e32 v83, v68, v68
	v_fmac_f32_e32 v83, v38, v38
	s_waitcnt lgkmcnt(0)
	v_fma_f32 v36, v40, v64, -v36
	v_fma_f32 v35, v41, v64, -v37
	ds_read2_b32 v[40:41], v69 offset0:64 offset1:96
	v_fmac_f32_e32 v83, v36, v36
	v_fmac_f32_e32 v83, v35, v35
	s_waitcnt lgkmcnt(0)
	v_fma_f32 v69, v42, v64, -v40
	v_fma_f32 v42, v43, v64, -v41
	ds_read2_b32 v[40:41], v71 offset1:32
	v_fmac_f32_e32 v83, v69, v69
	v_fmac_f32_e32 v83, v42, v42
	s_waitcnt lgkmcnt(0)
	v_fma_f32 v39, v44, v64, -v40
	v_fma_f32 v37, v45, v64, -v41
	ds_read2_b32 v[40:41], v71 offset0:64 offset1:96
	v_fmac_f32_e32 v83, v39, v39
	v_fmac_f32_e32 v83, v37, v37
	s_waitcnt lgkmcnt(0)
	v_fma_f32 v71, v46, v64, -v40
	v_fma_f32 v46, v47, v64, -v41
	ds_read2_b32 v[40:41], v73 offset1:32
	v_fmac_f32_e32 v83, v71, v71
	v_fmac_f32_e32 v83, v46, v46
	s_waitcnt lgkmcnt(0)
	v_fma_f32 v43, v16, v64, -v40
	v_fma_f32 v41, v17, v64, -v41
	ds_read2_b32 v[16:17], v73 offset0:64 offset1:96
	v_fmac_f32_e32 v83, v43, v43
	v_fmac_f32_e32 v83, v41, v41
	s_waitcnt lgkmcnt(0)
	v_fma_f32 v75, v18, v64, -v16
	v_fma_f32 v74, v19, v64, -v17
	ds_read2_b32 v[16:17], v72 offset1:32
	v_fmac_f32_e32 v83, v75, v75
	v_fmac_f32_e32 v83, v74, v74
	s_waitcnt lgkmcnt(0)
	v_fma_f32 v47, v20, v64, -v16
	v_fma_f32 v44, v21, v64, -v17
	ds_read2_b32 v[16:17], v72 offset0:64 offset1:96
	v_fmac_f32_e32 v83, v47, v47
	v_fmac_f32_e32 v83, v44, v44
	s_waitcnt lgkmcnt(0)
	v_fma_f32 v77, v22, v64, -v16
	v_fma_f32 v76, v23, v64, -v17
	ds_read2_b32 v[16:17], v70 offset1:32
	v_fmac_f32_e32 v83, v77, v77
	v_fmac_f32_e32 v83, v76, v76
	s_waitcnt lgkmcnt(0)
	v_fma_f32 v73, v24, v64, -v16
	v_fma_f32 v72, v25, v64, -v17
	ds_read2_b32 v[16:17], v70 offset0:64 offset1:96
	v_fmac_f32_e32 v83, v73, v73
	v_fmac_f32_e32 v83, v72, v72
	s_waitcnt lgkmcnt(0)
	v_fma_f32 v70, v26, v64, -v16
	v_fma_f32 v45, v27, v64, -v17
	ds_read2_b32 v[16:17], v82 offset1:32
	v_fmac_f32_e32 v83, v70, v70
	v_fmac_f32_e32 v83, v45, v45
	s_waitcnt lgkmcnt(0)
	v_fma_f32 v40, v28, v64, -v16
	v_fma_f32 v28, v29, v64, -v17
	ds_read2_b32 v[16:17], v82 offset0:64 offset1:96
	v_fmac_f32_e32 v83, v40, v40
	v_fmac_f32_e32 v83, v28, v28
	s_waitcnt lgkmcnt(0)
	v_fma_f32 v27, v30, v64, -v16
	v_fma_f32 v26, v31, v64, -v17
	ds_read2_b32 v[16:17], v81 offset1:32
	v_fmac_f32_e32 v83, v27, v27
	v_fmac_f32_e32 v83, v26, v26
	s_waitcnt lgkmcnt(0)
	v_fma_f32 v25, v0, v64, -v16
	v_fma_f32 v24, v1, v64, -v17
	ds_read2_b32 v[0:1], v81 offset0:64 offset1:96
	v_fmac_f32_e32 v83, v25, v25
	v_fmac_f32_e32 v83, v24, v24
	s_waitcnt lgkmcnt(0)
	v_fma_f32 v23, v2, v64, -v0
	v_fma_f32 v22, v3, v64, -v1
	ds_read2_b32 v[0:1], v80 offset1:32
	v_fmac_f32_e32 v83, v23, v23
	v_fmac_f32_e32 v83, v22, v22
	s_waitcnt lgkmcnt(0)
	v_fma_f32 v21, v4, v64, -v0
	v_fma_f32 v20, v5, v64, -v1
	ds_read2_b32 v[0:1], v80 offset0:64 offset1:96
	v_fmac_f32_e32 v83, v21, v21
	v_fmac_f32_e32 v83, v20, v20
	s_waitcnt lgkmcnt(0)
	v_pk_fma_f32 v[18:19], v[6:7], v[64:65], v[0:1] op_sel_hi:[1,0,1] neg_lo:[0,0,1] neg_hi:[0,0,1]
	s_nop 0
	v_pk_mul_f32 v[0:1], v[18:19], v[18:19]
	s_nop 0
	v_add_f32_e32 v0, v83, v0
	v_add_f32_e32 v2, v0, v1
	ds_read2_b32 v[0:1], v79 offset1:32
	s_waitcnt lgkmcnt(0)
; #define LAS __attribute__((address_space(3)))
; __device__ __forceinline__ unsigned cvt_pk_bf16(float lo, float hi) { unsigned r; asm volatile("v_cvt_pk_bf16_f32 %0, %1, %2" : "=v"(r) : "v"(lo), "v"(hi)); return r; }
; __device__ __forceinline__ void attn_unit(LAS unsigned char* lds, const bf16_t* __restrict__ U3, const bf16_t* __restrict__ VT, bf16_t* __restrict__ MIX, ...
;     ...
;         ss += __shfl_xor(ss, 32);
;         const float rs = rsqrtf(ss * (1.0f / 128.0f) + EPS) * 0.8f;
;         {
;             LAS unsigned char* stg = lds + 65536 + (w & 3) * 8704;
; #pragma unroll
;             for (int d0 = 0; d0 < 4; ++d0)
; #pragma unroll
;                 for (int rg = 0; rg < 4; ++rg) { const int dv = 32 * d0 + 8 * rg; const f32x4 gn = *(const f32x4*)(gain + dv + 4 * hi);
;                     u32x2 wv; wv.x = cvt_pk_bf16(o[d0][4 * rg] * rs * gn.x, o[d0][4 * rg + 1] * rs * gn.y); wv.y = cvt_pk_bf16(o[d0][4 * rg + 2] * rs * gn.z, o[d0][4 * rg + 3] * rs * gn.w);
;                     *(LAS u32x2*)(stg + r32 * 272 + (dv + 4 * hi) * 2) = wv; }
	v_pk_fma_f32 v[16:17], v[8:9], v[64:65], v[0:1] op_sel_hi:[1,0,1] neg_lo:[0,0,1] neg_hi:[0,0,1]
	s_nop 0
	v_pk_mul_f32 v[0:1], v[16:17], v[16:17]
	s_nop 0
	v_add_f32_e32 v0, v2, v0
	v_add_f32_e32 v2, v0, v1
	ds_read2_b32 v[0:1], v79 offset0:64 offset1:96
	s_waitcnt lgkmcnt(0)
	v_pk_fma_f32 v[8:9], v[10:11], v[64:65], v[0:1] op_sel_hi:[1,0,1] neg_lo:[0,0,1] neg_hi:[0,0,1]
	s_nop 0
	v_pk_mul_f32 v[0:1], v[8:9], v[8:9]
	v_mul_u32_u24_e32 v11, 0x110, v158
	v_add_f32_e32 v0, v2, v0
	v_add_f32_e32 v2, v0, v1
	ds_read2_b32 v[0:1], v78 offset1:32
	s_waitcnt lgkmcnt(0)
	v_pk_fma_f32 v[4:5], v[12:13], v[64:65], v[0:1] op_sel_hi:[1,0,1] neg_lo:[0,0,1] neg_hi:[0,0,1]
	s_nop 0
	v_pk_mul_f32 v[0:1], v[4:5], v[4:5]
	s_nop 0
	v_add_f32_e32 v0, v2, v0
	v_add_f32_e32 v2, v0, v1
	ds_read2_b32 v[0:1], v78 offset0:64 offset1:96
	s_waitcnt lgkmcnt(0)
	v_pk_fma_f32 v[6:7], v[14:15], v[64:65], v[0:1] op_sel_hi:[1,0,1] neg_lo:[0,0,1] neg_hi:[0,0,1]
	s_nop 0
	v_pk_mul_f32 v[0:1], v[6:7], v[6:7]
	s_nop 0
	v_add_f32_e32 v0, v2, v0
	v_add_f32_e32 v0, v0, v1
	ds_bpermute_b32 v1, v145, v0
	s_waitcnt lgkmcnt(0)
	v_add_f32_e32 v0, v0, v1
	v_fmamk_f32 v0, v0, 0x3c000000, v205
	v_cmp_gt_f32_e32 vcc, s92, v0
	v_mul_f32_e32 v1, 0x4b800000, v0
	s_nop 0
	v_cndmask_b32_e32 v0, v0, v1, vcc
	v_rsq_f32_e32 v0, v0
	s_nop 0
	v_mul_f32_e32 v1, 0x45800000, v0
	v_cndmask_b32_e32 v0, v0, v1, vcc
	v_mul_f32_e32 v10, 0x3f4ccccd, v0
	global_load_dwordx4 v[0:3], v160, s[94:95]
	v_mul_f32_e32 v12, v66, v10
	s_waitcnt vmcnt(0)
	v_mul_f32_e32 v0, v0, v12
	v_mul_f32_e32 v12, v65, v10
	v_mul_f32_e32 v1, v1, v12
	v_cvt_pk_bf16_f32 v12, v0, v1
	v_mul_f32_e32 v0, v50, v10
	v_mul_f32_e32 v0, v2, v0
	v_mul_f32_e32 v1, v51, v10
	v_mul_f32_e32 v1, v3, v1
	v_cvt_pk_bf16_f32 v13, v0, v1
	v_add3_u32 v0, s10, v11, v157
	ds_write_b64 v0, v[12:13]
	global_load_dwordx4 v[12:15], v160, s[94:95] offset:32
	v_mul_f32_e32 v1, v48, v10
	v_mul_f32_e32 v2, v49, v10
	v_mul_f32_e32 v3, v53, v10
	s_waitcnt vmcnt(0)
	v_mul_f32_e32 v1, v12, v1
	v_mul_f32_e32 v2, v13, v2
	v_cvt_pk_bf16_f32 v2, v1, v2
	v_mul_f32_e32 v1, v52, v10
	v_mul_f32_e32 v3, v15, v3
	v_mul_f32_e32 v1, v14, v1
	v_cvt_pk_bf16_f32 v3, v1, v3
	global_load_dwordx4 v[12:15], v160, s[94:95] offset:64
	ds_write_b64 v0, v[2:3] offset:16
	v_mul_f32_e32 v1, v55, v10
	v_mul_f32_e32 v2, v54, v10
	v_mul_f32_e32 v3, v58, v10
	s_waitcnt vmcnt(0)
	v_mul_f32_e32 v1, v12, v1
	v_mul_f32_e32 v2, v13, v2
	v_cvt_pk_bf16_f32 v2, v1, v2
	v_mul_f32_e32 v1, v67, v10
	v_mul_f32_e32 v3, v15, v3
	v_mul_f32_e32 v1, v14, v1
	v_cvt_pk_bf16_f32 v3, v1, v3
	global_load_dwordx4 v[12:15], v160, s[94:95] offset:96
	ds_write_b64 v0, v[2:3] offset:32
	v_mul_f32_e32 v1, v57, v10
	v_mul_f32_e32 v2, v56, v10
	v_mul_f32_e32 v3, v60, v10
	s_waitcnt vmcnt(0)
	v_mul_f32_e32 v1, v1, v12
	v_mul_f32_e32 v2, v2, v13
	v_cvt_pk_bf16_f32 v2, v1, v2
	v_mul_f32_e32 v1, v61, v10
	v_mul_f32_e32 v3, v3, v15
	v_mul_f32_e32 v1, v1, v14
	v_cvt_pk_bf16_f32 v3, v1, v3
	global_load_dwordx4 v[12:15], v160, s[94:95] offset:128
	ds_write_b64 v0, v[2:3] offset:48
	v_mul_f32_e32 v1, v59, v10
	v_mul_f32_e32 v2, v32, v10
	v_mul_f32_e32 v3, v62, v10
	s_waitcnt vmcnt(0)
	v_mul_f32_e32 v1, v1, v12
	v_mul_f32_e32 v2, v2, v13
	v_cvt_pk_bf16_f32 v2, v1, v2
	v_mul_f32_e32 v1, v63, v10
	v_mul_f32_e32 v3, v3, v15
	v_mul_f32_e32 v1, v1, v14
	v_cvt_pk_bf16_f32 v3, v1, v3
	global_load_dwordx4 v[12:15], v160, s[94:95] offset:160
	ds_write_b64 v0, v[2:3] offset:64
	v_mul_f32_e32 v1, v34, v10
	v_mul_f32_e32 v2, v33, v10
	v_mul_f32_e32 v3, v38, v10
	s_waitcnt vmcnt(0)
	v_mul_f32_e32 v1, v1, v12
	v_mul_f32_e32 v2, v2, v13
	v_cvt_pk_bf16_f32 v2, v1, v2
	v_mul_f32_e32 v1, v68, v10
	v_mul_f32_e32 v3, v3, v15
	v_mul_f32_e32 v1, v1, v14
	v_cvt_pk_bf16_f32 v3, v1, v3
	global_load_dwordx4 v[12:15], v160, s[94:95] offset:192
	ds_write_b64 v0, v[2:3] offset:80
	v_mul_f32_e32 v1, v36, v10
	v_mul_f32_e32 v2, v35, v10
	v_mul_f32_e32 v3, v42, v10
	s_waitcnt vmcnt(0)
	v_mul_f32_e32 v1, v1, v12
	v_mul_f32_e32 v2, v2, v13
	v_cvt_pk_bf16_f32 v2, v1, v2
	v_mul_f32_e32 v1, v69, v10
	v_mul_f32_e32 v3, v3, v15
	v_mul_f32_e32 v1, v1, v14
	v_cvt_pk_bf16_f32 v3, v1, v3
	global_load_dwordx4 v[12:15], v160, s[94:95] offset:224
	ds_write_b64 v0, v[2:3] offset:96
	v_mul_f32_e32 v1, v39, v10
	v_mul_f32_e32 v2, v37, v10
	v_mul_f32_e32 v3, v46, v10
	s_waitcnt vmcnt(0)
	v_mul_f32_e32 v1, v1, v12
	v_mul_f32_e32 v2, v2, v13
	v_cvt_pk_bf16_f32 v2, v1, v2
	v_mul_f32_e32 v1, v71, v10
	v_mul_f32_e32 v3, v3, v15
	v_mul_f32_e32 v1, v1, v14
	v_cvt_pk_bf16_f32 v3, v1, v3
	global_load_dwordx4 v[12:15], v160, s[94:95] offset:256
	ds_write_b64 v0, v[2:3] offset:112
	v_mul_f32_e32 v1, v43, v10
	v_mul_f32_e32 v2, v41, v10
	v_mul_f32_e32 v3, v74, v10
	s_waitcnt vmcnt(0)
; #define LAS __attribute__((address_space(3)))
; __device__ __forceinline__ unsigned cvt_pk_bf16(float lo, float hi) { unsigned r; asm volatile("v_cvt_pk_bf16_f32 %0, %1, %2" : "=v"(r) : "v"(lo), "v"(hi)); return r; }
; __device__ __forceinline__ void attn_unit(LAS unsigned char* lds, const bf16_t* __restrict__ U3, const bf16_t* __restrict__ VT, bf16_t* __restrict__ MIX, ...
;     ...
;                 for (int rg = 0; rg < 4; ++rg) { const int dv = 32 * d0 + 8 * rg; const f32x4 gn = *(const f32x4*)(gain + dv + 4 * hi);
;                     u32x2 wv; wv.x = cvt_pk_bf16(o[d0][4 * rg] * rs * gn.x, o[d0][4 * rg + 1] * rs * gn.y); wv.y = cvt_pk_bf16(o[d0][4 * rg + 2] * rs * gn.z, o[d0][4 * rg + 3] * rs * gn.w);
;                     *(LAS u32x2*)(stg + r32 * 272 + (dv + 4 * hi) * 2) = wv; }
;             asm volatile("s_waitcnt lgkmcnt(0)" ::: "memory");
;             bf16_t* op = MIX + (size_t)(rowbase + qw0 - NMETA + (lane >> 4)) * D + h * 128 + (lane & 15) * 8;
; #pragma unroll
;             for (int i = 0; i < 8; ++i) { const u32x4 v = *(const LAS u32x4*)(stg + (i * 4 + (lane >> 4)) * 272 + (lane & 15) * 16); *(u32x4*)(op + (size_t)(i * 4) * D) = v; }
	v_mul_f32_e32 v1, v1, v12
	v_mul_f32_e32 v2, v2, v13
	v_cvt_pk_bf16_f32 v2, v1, v2
	v_mul_f32_e32 v1, v75, v10
	v_mul_f32_e32 v3, v3, v15
	v_mul_f32_e32 v1, v1, v14
	v_cvt_pk_bf16_f32 v3, v1, v3
	global_load_dwordx4 v[12:15], v160, s[94:95] offset:288
	ds_write_b64 v0, v[2:3] offset:128
	v_mul_f32_e32 v1, v47, v10
	v_mul_f32_e32 v2, v44, v10
	v_mul_f32_e32 v3, v76, v10
	s_waitcnt vmcnt(0)
	v_mul_f32_e32 v1, v1, v12
	v_mul_f32_e32 v2, v2, v13
	v_cvt_pk_bf16_f32 v2, v1, v2
	v_mul_f32_e32 v1, v77, v10
	v_mul_f32_e32 v3, v3, v15
	v_mul_f32_e32 v1, v1, v14
	v_cvt_pk_bf16_f32 v3, v1, v3
	global_load_dwordx4 v[12:15], v160, s[94:95] offset:320
	ds_write_b64 v0, v[2:3] offset:144
	v_mul_f32_e32 v1, v73, v10
	v_mul_f32_e32 v2, v72, v10
	v_mul_f32_e32 v3, v45, v10
	s_waitcnt vmcnt(0)
	v_mul_f32_e32 v1, v1, v12
	v_mul_f32_e32 v2, v2, v13
	v_cvt_pk_bf16_f32 v2, v1, v2
	v_mul_f32_e32 v1, v70, v10
	v_mul_f32_e32 v3, v3, v15
	v_mul_f32_e32 v1, v1, v14
	v_cvt_pk_bf16_f32 v3, v1, v3
	global_load_dwordx4 v[12:15], v160, s[94:95] offset:352
	ds_write_b64 v0, v[2:3] offset:160
	v_mul_f32_e32 v1, v40, v10
	v_mul_f32_e32 v2, v28, v10
	v_mul_f32_e32 v3, v26, v10
	s_waitcnt vmcnt(0)
	v_mul_f32_e32 v1, v1, v12
	v_mul_f32_e32 v2, v2, v13
	v_cvt_pk_bf16_f32 v2, v1, v2
	v_mul_f32_e32 v1, v27, v10
	v_mul_f32_e32 v3, v3, v15
	v_mul_f32_e32 v1, v1, v14
	v_cvt_pk_bf16_f32 v3, v1, v3
	global_load_dwordx4 v[12:15], v160, s[94:95] offset:384
	ds_write_b64 v0, v[2:3] offset:176
	v_mul_f32_e32 v1, v25, v10
	v_mul_f32_e32 v2, v24, v10
	v_mul_f32_e32 v3, v22, v10
	s_waitcnt vmcnt(0)
	v_mul_f32_e32 v1, v1, v12
	v_mul_f32_e32 v2, v2, v13
	v_cvt_pk_bf16_f32 v2, v1, v2
	v_mul_f32_e32 v1, v23, v10
	v_mul_f32_e32 v3, v3, v15
	v_mul_f32_e32 v1, v1, v14
	v_cvt_pk_bf16_f32 v3, v1, v3
	global_load_dwordx4 v[12:15], v160, s[94:95] offset:416
	ds_write_b64 v0, v[2:3] offset:192
	v_mul_f32_e32 v1, v21, v10
	v_mul_f32_e32 v2, v20, v10
	v_mul_f32_e32 v3, v19, v10
	s_waitcnt vmcnt(0)
	v_mul_f32_e32 v1, v1, v12
	v_mul_f32_e32 v2, v2, v13
	v_cvt_pk_bf16_f32 v2, v1, v2
	v_mul_f32_e32 v1, v18, v10
	v_mul_f32_e32 v3, v3, v15
	v_mul_f32_e32 v1, v1, v14
	v_cvt_pk_bf16_f32 v3, v1, v3
	global_load_dwordx4 v[12:15], v160, s[94:95] offset:448
	ds_write_b64 v0, v[2:3] offset:208
	v_mul_f32_e32 v1, v16, v10
	v_mul_f32_e32 v2, v17, v10
	v_mul_f32_e32 v3, v9, v10
	s_waitcnt vmcnt(0)
	v_mul_f32_e32 v1, v1, v12
	v_mul_f32_e32 v2, v2, v13
	v_cvt_pk_bf16_f32 v2, v1, v2
	v_mul_f32_e32 v1, v8, v10
	v_mul_f32_e32 v3, v3, v15
	v_mul_f32_e32 v1, v1, v14
	v_cvt_pk_bf16_f32 v3, v1, v3
	global_load_dwordx4 v[12:15], v160, s[94:95] offset:480
	ds_write_b64 v0, v[2:3] offset:224
	v_mul_f32_e32 v1, v4, v10
	v_mul_f32_e32 v2, v5, v10
	v_mul_f32_e32 v3, v7, v10
	s_waitcnt vmcnt(0)
	v_mul_f32_e32 v1, v1, v12
	v_mul_f32_e32 v2, v2, v13
	v_cvt_pk_bf16_f32 v2, v1, v2
	v_mul_f32_e32 v1, v6, v10
	v_mul_f32_e32 v3, v3, v15
	v_mul_f32_e32 v1, v1, v14
	v_cvt_pk_bf16_f32 v3, v1, v3
	ds_write_b64 v0, v[2:3] offset:240
	v_or_b32_e32 v0, s63, v156
	v_add_u32_e32 v0, s62, v0
	v_ashrrev_i32_e32 v1, 31, v0
	v_lshlrev_b64 v[0:1], 11, v[0:1]
	v_lshlrev_b32_e32 v2, 4, v155
	v_lshl_add_u64 v[0:1], s[22:23], 0, v[0:1]
	v_and_b32_e32 v160, 0xf0, v2
	v_lshl_add_u64 v[4:5], v[0:1], 0, v[160:161]
	v_mul_u32_u24_e32 v0, 0x110, v156
	s_waitcnt lgkmcnt(0)
	v_add3_u32 v8, s10, v160, v0
	ds_read_b128 v[0:3], v8
	s_movk_i32 s10, 0x2000
	v_add_co_u32_e32 v6, vcc, s10, v4
	s_movk_i32 s10, 0x4000
	s_waitcnt lgkmcnt(0)
	global_store_dwordx4 v[4:5], v[0:3], off nt
	ds_read_b128 v[0:3], v8 offset:1088
	v_addc_co_u32_e32 v7, vcc, 0, v5, vcc
	s_waitcnt lgkmcnt(0)
	global_store_dwordx4 v[6:7], v[0:3], off nt
	ds_read_b128 v[0:3], v8 offset:2176
	v_add_co_u32_e32 v6, vcc, s10, v4
	s_movk_i32 s10, 0x6000
	s_nop 0
	v_addc_co_u32_e32 v7, vcc, 0, v5, vcc
	s_waitcnt lgkmcnt(0)
	global_store_dwordx4 v[6:7], v[0:3], off nt
	ds_read_b128 v[0:3], v8 offset:3264
	v_add_co_u32_e32 v6, vcc, s10, v4
	s_mov_b32 s10, 0x8000
	s_nop 0
	v_addc_co_u32_e32 v7, vcc, 0, v5, vcc
	s_waitcnt lgkmcnt(0)
	global_store_dwordx4 v[6:7], v[0:3], off nt
	ds_read_b128 v[0:3], v8 offset:4352
	v_add_co_u32_e32 v6, vcc, s10, v4
	s_nop 1
	v_addc_co_u32_e32 v7, vcc, 0, v5, vcc
	s_waitcnt lgkmcnt(0)
	global_store_dwordx4 v[6:7], v[0:3], off nt
	ds_read_b128 v[0:3], v8 offset:5440
	v_add_co_u32_e32 v6, vcc, 0xa000, v4
	s_nop 1
	v_addc_co_u32_e32 v7, vcc, 0, v5, vcc
	s_waitcnt lgkmcnt(0)
	global_store_dwordx4 v[6:7], v[0:3], off nt
	ds_read_b128 v[0:3], v8 offset:6528
	v_add_co_u32_e32 v6, vcc, 0xc000, v4
	s_nop 1
	v_addc_co_u32_e32 v7, vcc, 0, v5, vcc
	s_waitcnt lgkmcnt(0)
	global_store_dwordx4 v[6:7], v[0:3], off nt
	ds_read_b128 v[0:3], v8 offset:7616
	v_add_co_u32_e32 v4, vcc, 0xe000, v4
	s_nop 1
	v_addc_co_u32_e32 v5, vcc, 0, v5, vcc
	s_waitcnt lgkmcnt(0)
	global_store_dwordx4 v[4:5], v[0:3], off nt
	s_branch .LBB0_498
